# pa_tile_decode_constant_divisors
# speedup vs baseline: 1.0073x; 1.0073x over previous
;     __device__ bool next(int i, Unit& u) const {
;         const long L = (long)i * G + c; if (L >= nwg) return false;
;         int wgid = (int)L; { const int q = nwg / NXCD, r = nwg % NXCD, xcd = wgid % NXCD, off = wgid / NXCD; wgid = (xcd < r ? xcd * (q + 1) : r * (q + 1) + (xcd - r) * q) + off; }
;         const int nig = WGM * nN, gid = wgid / nig, fm = gid * WGM, gsz = (nM - fm) < WGM ? (nM - fm) : WGM;
;         u.pm = fm + ((wgid % nig) % gsz); u.pn = (wgid % nig) / gsz; return true;
;     }
.LBB0_169:
	s_add_i32 s70, s70, 1
	s_mul_i32 s0, s70, s56
	s_mul_hi_u32 s1, s70, s50
	s_add_i32 s1, s1, s0
	s_mul_i32 s0, s70, s50
	s_add_u32 s4, s0, s2
	s_addc_u32 s5, s1, s57
	s_cmp_lt_u32 s4, 0xfc0
	s_cselect_b64 s[0:1], -1, 0
	s_cselect_b64 vcc, 0, -1
	s_cbranch_vccnz .LBB0_171
	s_lshr_b32 s5, s4, 3
	s_mul_i32 s30, s5, 0x30d
	s_lshr_b32 s30, s30, 16
	s_mul_i32 s31, s30, 0x54
	s_sub_i32 s5, s5, s31
	s_and_b32 s31, s5, 3
	s_lshl_b32 s34, s30, 2
	s_add_i32 s34, s34, s31
	s_lshl_b32 s34, s34, 3
	s_and_b32 s31, s4, 7
	s_or_b32 s34, s34, s31
	s_lshr_b32 s30, s5, 2
